# RB scan: chunk-prefix LDS operand reads issued in batches with counted waits (on top of the fix-up / sample-GEMM de-serialisation)
# speedup vs baseline: 1.0064x; 1.0007x over previous
.LBB0_543:
	s_or_b64 exec, exec, s[8:9]
	s_waitcnt vmcnt(0) lgkmcnt(0)
	v_pk_fma_f32 v[2:3], v[66:67], 0, v[70:71] op_sel_hi:[1,0,1]
	v_pk_fma_f32 v[6:7], v[64:65], 0, v[68:69] op_sel_hi:[1,0,1]
	v_pk_fma_f32 v[2:3], v[2:3], v[58:59], v[62:63]
	v_pk_mul_f32 v[104:105], v[66:67], v[58:59]
	v_pk_mul_f32 v[106:107], v[64:65], v[56:57]
	v_pk_fma_f32 v[2:3], v[2:3], v[50:51], v[54:55]
	v_pk_fma_f32 v[6:7], v[6:7], v[56:57], v[60:61]
	v_pk_mul_f32 v[104:105], v[104:105], v[50:51]
	v_pk_mul_f32 v[106:107], v[106:107], v[48:49]
	v_pk_fma_f32 v[2:3], v[2:3], v[42:43], v[46:47]
	v_pk_fma_f32 v[6:7], v[6:7], v[48:49], v[52:53]
	v_pk_mul_f32 v[104:105], v[104:105], v[42:43]
	v_pk_mul_f32 v[106:107], v[106:107], v[40:41]
	v_pk_fma_f32 v[2:3], v[2:3], v[34:35], v[38:39]
	v_pk_fma_f32 v[6:7], v[6:7], v[40:41], v[44:45]
	v_pk_mul_f32 v[104:105], v[104:105], v[34:35]
	v_pk_mul_f32 v[106:107], v[106:107], v[32:33]
	v_pk_fma_f32 v[2:3], v[2:3], v[26:27], v[30:31]
	v_pk_fma_f32 v[6:7], v[6:7], v[32:33], v[36:37]
	v_pk_mul_f32 v[104:105], v[104:105], v[26:27]
	v_pk_mul_f32 v[106:107], v[106:107], v[24:25]
	v_pk_fma_f32 v[2:3], v[2:3], v[18:19], v[22:23]
	v_lshl_add_u32 v0, v85, 14, 0
	v_pk_fma_f32 v[6:7], v[6:7], v[24:25], v[28:29]
	v_pk_mul_f32 v[108:109], v[104:105], v[18:19]
	v_pk_mul_f32 v[112:113], v[106:107], v[16:17]
	v_pk_fma_f32 v[106:107], v[2:3], v[10:11], v[14:15]
	v_and_b32_e32 v2, 0xff, v100
	v_pk_fma_f32 v[6:7], v[6:7], v[16:17], v[20:21]
	v_pk_mul_f32 v[110:111], v[108:109], v[10:11]
	v_pk_mul_f32 v[108:109], v[112:113], v[8:9]
	v_lshl_add_u32 v2, v2, 4, v0
	v_lshl_add_u32 v0, v83, 4, v0
	v_pk_fma_f32 v[104:105], v[6:7], v[8:9], v[12:13]
	ds_write_b128 v2, v[108:111]
	ds_write_b128 v2, v[104:107] offset:4096
	ds_write_b128 v2, v[72:75] offset:8192
	ds_write_b128 v2, v[76:79] offset:12288
	s_waitcnt lgkmcnt(0)
	s_barrier
	v_cmp_ne_u32_e32 vcc, 0, v102
	ds_read_b128 v[172:175], v0 offset:8192
	ds_read_b128 v[176:179], v0 offset:12288
	ds_read_b128 v[180:183], v0 offset:8448
	ds_read_b128 v[184:187], v0 offset:12544
	ds_read_b128 v[188:191], v0 offset:8704
	ds_read_b128 v[192:195], v0 offset:12800
	ds_read_b128 v[200:203], v0 offset:8960
	ds_read_b128 v[204:207], v0 offset:13056
	ds_read_b128 v[208:211], v0 offset:9216
	ds_read_b128 v[212:215], v0 offset:13312
	ds_read_b128 v[232:235], v0 offset:9472
	ds_read_b128 v[236:239], v0 offset:13568
	s_waitcnt lgkmcnt(10)
	v_pk_fma_f32 v[2:3], v[174:175], 0, v[178:179] op_sel_hi:[1,0,1]
	v_pk_fma_f32 v[6:7], v[172:173], 0, v[176:177] op_sel_hi:[1,0,1]
	s_waitcnt lgkmcnt(8)
	v_pk_fma_f32 v[2:3], v[2:3], v[182:183], v[186:187]
	v_pk_fma_f32 v[6:7], v[6:7], v[180:181], v[184:185]
	s_waitcnt lgkmcnt(6)
	v_pk_fma_f32 v[2:3], v[2:3], v[190:191], v[194:195]
	v_pk_fma_f32 v[6:7], v[6:7], v[188:189], v[192:193]
	s_waitcnt lgkmcnt(4)
	v_pk_fma_f32 v[2:3], v[2:3], v[202:203], v[206:207]
	v_pk_fma_f32 v[6:7], v[6:7], v[200:201], v[204:205]
	s_waitcnt lgkmcnt(2)
	v_pk_fma_f32 v[2:3], v[2:3], v[210:211], v[214:215]
	v_pk_fma_f32 v[6:7], v[6:7], v[208:209], v[212:213]
	s_waitcnt lgkmcnt(0)
	v_pk_fma_f32 v[2:3], v[2:3], v[234:235], v[238:239]
	v_pk_fma_f32 v[6:7], v[6:7], v[232:233], v[236:237]
	ds_read_b128 v[172:175], v0 offset:9728
	ds_read_b128 v[176:179], v0 offset:13824
	ds_read_b128 v[180:183], v0 offset:9984
	ds_read_b128 v[184:187], v0 offset:14080
	ds_read_b128 v[188:191], v0 offset:10240
	ds_read_b128 v[192:195], v0 offset:14336
	ds_read_b128 v[200:203], v0 offset:10496
	ds_read_b128 v[204:207], v0 offset:14592
	ds_read_b128 v[208:211], v0 offset:10752
	ds_read_b128 v[212:215], v0 offset:14848
	s_waitcnt lgkmcnt(8)
	v_pk_fma_f32 v[2:3], v[2:3], v[174:175], v[178:179]
	v_pk_fma_f32 v[6:7], v[6:7], v[172:173], v[176:177]
	s_waitcnt lgkmcnt(6)
	v_pk_fma_f32 v[2:3], v[2:3], v[182:183], v[186:187]
	v_pk_fma_f32 v[6:7], v[6:7], v[180:181], v[184:185]
	s_waitcnt lgkmcnt(4)
	v_pk_fma_f32 v[2:3], v[2:3], v[190:191], v[194:195]
	v_pk_fma_f32 v[6:7], v[6:7], v[188:189], v[192:193]
	s_waitcnt lgkmcnt(2)
	v_pk_fma_f32 v[2:3], v[2:3], v[202:203], v[206:207]
	v_pk_fma_f32 v[6:7], v[6:7], v[200:201], v[204:205]
	s_waitcnt lgkmcnt(0)
	v_pk_fma_f32 v[2:3], v[2:3], v[210:211], v[214:215]
	v_pk_fma_f32 v[6:7], v[6:7], v[208:209], v[212:213]
	ds_read_b128 v[172:175], v0 offset:11008
	ds_read_b128 v[176:179], v0 offset:15104
	ds_read_b128 v[180:183], v0 offset:11264
	ds_read_b128 v[184:187], v0 offset:15360
	ds_read_b128 v[188:191], v0 offset:11520
	ds_read_b128 v[192:195], v0 offset:15616
	ds_read_b128 v[200:203], v0 offset:11776
	ds_read_b128 v[204:207], v0 offset:15872
	ds_read_b128 v[208:211], v0 offset:12032
	ds_read_b128 v[212:215], v0 offset:16128
	s_waitcnt lgkmcnt(8)
	v_pk_fma_f32 v[2:3], v[2:3], v[174:175], v[178:179]
	v_pk_fma_f32 v[6:7], v[6:7], v[172:173], v[176:177]
	s_waitcnt lgkmcnt(6)
	v_pk_fma_f32 v[2:3], v[2:3], v[182:183], v[186:187]
	v_pk_fma_f32 v[6:7], v[6:7], v[180:181], v[184:185]
	s_waitcnt lgkmcnt(4)
	v_pk_fma_f32 v[2:3], v[2:3], v[190:191], v[194:195]
	v_pk_fma_f32 v[6:7], v[6:7], v[188:189], v[192:193]
	s_waitcnt lgkmcnt(2)
	v_pk_fma_f32 v[2:3], v[2:3], v[202:203], v[206:207]
	v_pk_fma_f32 v[6:7], v[6:7], v[200:201], v[204:205]
	s_waitcnt lgkmcnt(0)
	v_pk_fma_f32 v[74:75], v[2:3], v[210:211], v[214:215]
	v_pk_fma_f32 v[72:73], v[6:7], v[208:209], v[212:213]
	s_and_saveexec_b64 s[2:3], vcc
	s_cbranch_execz .LBB0_547
	s_mov_b64 s[4:5], 0
	v_mov_b32_e32 v2, v102
